# HGRN2 chunk scan: decay-pass q re-reads issued together ahead of the stores; end-of-chunk barrier kept only for the last chunk
# speedup vs baseline: 1.0009x; 1.0009x over previous
.LBB0_449:
	s_or_b64 exec, exec, s[4:5]
	s_add_i32 s31, s31, 64
	v_subrev_u32_e32 v0, 64, v0
	v_subrev_u32_e32 v87, 64, v87
	v_subrev_u32_e32 v89, 64, v89
	s_cmpk_lg_i32 s31, 0x1100
	v_subrev_u32_e32 v91, 64, v91
	s_waitcnt lgkmcnt(0)
	s_cbranch_scc1 .LBB0_450
	s_barrier
	s_branch .LBB0_438
